# priority window shift: MLA fast stage raises s_setprio right after issuing the tile loads (before the vmcnt/ds_write ladder) instead of after it
# speedup vs baseline: 1.0007x; 1.0007x over previous
; #define MFMA32(a, b, c) __builtin_amdgcn_mfma_f32_32x32x16_bf16((a), (b), (c), 0, 0, 0)
; DI unsigned pk_bf16(float lo, float hi) { f32x2 v = {lo, hi}; bf2_t b = __builtin_convertvector(v, bf2_t); return __builtin_bit_cast(unsigned, b); }
; DI int crow(int i, int h) { return (i & 3) + 8 * (i >> 2) + 4 * h; }
; DI float fast_exp2(float x) { return __builtin_amdgcn_exp2f(x); }
; template <int DQK, bool SB, bool SMAX>
; DI void attn_item(const Params& p, char* smem, int bh, int qb, float Mb) {
;     ...
; #pragma unroll
;       for (int ks = 0; ks < NKS; ++ks)
; #pragma unroll
;         for (int kb = 0; kb < 2; ++kb) {
;           const bf16x8 a = *(const bf16x8*)(kc + (kb * 32 + r) * KSTR + ks * 16 + h * 8);
;           st[kb] = MFMA32(a, qf[ks], st[kb]);
;         }
;     }
;     __builtin_amdgcn_sched_barrier(0);
;     AT_WRITE(0, st2 ^ 1)
;     AT_LOAD(0, (it + 2 < nt) ? it + 2 : nt - 1)
;     if (active) {
;       const bool diag = (kb0 + 64 > qw0);
;       bf16x8 pk[4];
;       if (!SB) {
;         if (diag) {
; #pragma unroll
;           for (int kb = 0; kb < 2; ++kb)
; #pragma unroll
;             for (int i = 0; i < 16; ++i) { const int key = kb0 + kb * 32 + crow(i, h); if (key > query) st[kb][i] = -__builtin_huge_valf(); }
;         }
;         if (SMAX) {
;           float ps = 0.f;
; #pragma unroll
;           for (int kb = 0; kb < 2; ++kb)
; #pragma unroll
;             for (int i = 0; i < 16; ++i) { const float pv = fast_exp2(st[kb][i]); st[kb][i] = pv; ps += pv; }
;           lsum += ps;
;     ...
; #pragma unroll
;       for (int kb = 0; kb < 2; ++kb)
; #pragma unroll
;         for (int s = 0; s < 2; ++s) {
;           u32x4 w;
; #pragma unroll
;           for (int e = 0; e < 4; ++e) w[e] = pk_bf16(st[kb][8 * s + 2 * e], st[kb][8 * s + 2 * e + 1]);
;           pk[kb * 2 + s] = __builtin_bit_cast(bf16x8, w);
;         }
; #pragma unroll
;       for (int kk = 0; kk < 4; ++kk)
; #pragma unroll
;         for (int db = 0; db < 2; ++db) {
;           const s16x4 v0 = __builtin_amdgcn_ds_read_tr16_b64_v4i16((lds_s16x4*)(vc + voff + (16 * kk) * VSTR + 32 * db));
;           const s16x4 v1 = __builtin_amdgcn_ds_read_tr16_b64_v4i16((lds_s16x4*)(vc + voff + (16 * kk + 8) * VSTR + 32 * db));
;           const bf16x8 vf = __builtin_shufflevector(v0, v1, 0, 1, 2, 3, 4, 5, 6, 7);
;           O[db] = MFMA32(vf, pk[kk], O[db]);
;         }
.Lt15_loop:
	s_setprio 0
	ds_read_b128 v[216:219], v153 offset:13312
	ds_read_b128 v[220:223], v153 offset:19968
	ds_read_b128 v[228:231], v153 offset:13344
	ds_read_b64_tr_b16 v[236:237], v154 offset:26624
	ds_read_b64_tr_b16 v[238:239], v154 offset:27776
	ds_read_b64_tr_b16 v[244:245], v154 offset:26688
	ds_read_b64_tr_b16 v[246:247], v154 offset:27840
	ds_read_b64_tr_b16 v[248:249], v154 offset:28928
	ds_read_b64_tr_b16 v[250:251], v154 offset:30080
	s_min_i32 s2, s14, s4
	s_mul_i32 s3, s2, 0x3000
	s_add_u32 s30, s22, s3
	s_addc_u32 s31, s23, 0
	s_add_u32 s34, s30, 0x1000
	s_addc_u32 s35, s31, 0
	s_add_i32 s3, s14, -1
	s_min_i32 s3, s3, s4
	s_lshl_b32 s3, s3, 13
	s_add_u32 s36, s38, s3
	s_addc_u32 s37, s39, 0
	global_load_dwordx4 v[132:135], v174, s[30:31] offset:-4096
	global_load_dwordx4 v[136:139], v174, s[30:31]
	global_load_dwordx4 v[140:143], v174, s[34:35]
	global_load_dwordx4 v[144:147], v174, s[36:37] offset:-4096
	global_load_dwordx4 v[148:151], v174, s[36:37]
	s_setprio 2
	s_waitcnt vmcnt(9)
	ds_write_b128 v206, v[112:115]
	s_waitcnt vmcnt(8)
	ds_write_b128 v207, v[116:119]
	s_waitcnt vmcnt(7)
	ds_write_b128 v208, v[120:123]
	s_waitcnt vmcnt(6)
	ds_write_b128 v203, v[124:127] offset:35840
	s_waitcnt vmcnt(5)
	ds_write_b128 v203, v[128:131] offset:40448
	v_exp_f32_e32 v48, v48
	v_exp_f32_e32 v49, v49
	v_exp_f32_e32 v50, v50
	v_exp_f32_e32 v51, v51
	s_waitcnt lgkmcnt(13)
	v_mfma_f32_32x32x16_bf16 v[0:15], v[216:219], v[80:83], 0
	ds_read_b128 v[216:219], v153 offset:20000
	v_exp_f32_e32 v52, v52
	v_add_f32_e32 v224, v49, v48
	v_cvt_pk_bf16_f32 v188, v48, v49
	v_exp_f32_e32 v53, v53
	s_waitcnt lgkmcnt(13)
	v_mfma_f32_32x32x16_bf16 v[156:171], v[220:223], v[80:83], 0
	ds_read_b128 v[220:223], v153 offset:13376
	v_add_f32_e32 v224, v50, v224
	v_exp_f32_e32 v54, v54
	v_add_f32_e32 v224, v51, v224
	v_cvt_pk_bf16_f32 v189, v50, v51
	s_waitcnt lgkmcnt(13)
	v_mfma_f32_32x32x16_bf16 v[0:15], v[228:231], v[84:87], v[0:15]
	ds_read_b128 v[228:231], v153 offset:20032
	v_exp_f32_e32 v55, v55
	v_add_f32_e32 v224, v52, v224
	v_exp_f32_e32 v56, v56
	v_add_f32_e32 v224, v53, v224
	s_waitcnt lgkmcnt(2)
	v_mfma_f32_32x32x16_bf16 v[156:171], v[216:219], v[84:87], v[156:171]
	ds_read_b128 v[216:219], v153 offset:13408
	v_cvt_pk_bf16_f32 v190, v52, v53
	v_exp_f32_e32 v57, v57
	v_add_f32_e32 v224, v54, v224
	v_exp_f32_e32 v58, v58
	s_waitcnt lgkmcnt(2)
	v_mfma_f32_32x32x16_bf16 v[0:15], v[220:223], v[88:91], v[0:15]
	ds_read_b128 v[220:223], v153 offset:20064
	v_add_f32_e32 v224, v55, v224
	v_cvt_pk_bf16_f32 v191, v54, v55
	v_exp_f32_e32 v59, v59
	v_add_f32_e32 v224, v56, v224
	s_nop 0
	v_mfma_f32_32x32x16_bf16 v[32:47], v[236:239], v[188:191], v[32:47]
	ds_read_b64_tr_b16 v[236:237], v154 offset:28992
	ds_read_b64_tr_b16 v[238:239], v154 offset:30144
	v_exp_f32_e32 v60, v60
	v_add_f32_e32 v224, v57, v224
	v_cvt_pk_bf16_f32 v192, v56, v57
	v_exp_f32_e32 v61, v61
	v_mfma_f32_32x32x16_bf16 v[16:31], v[244:247], v[188:191], v[16:31]
	ds_read_b64_tr_b16 v[244:245], v154 offset:31232
	ds_read_b64_tr_b16 v[246:247], v154 offset:32384
	v_add_f32_e32 v224, v58, v224
	v_exp_f32_e32 v62, v62
	v_add_f32_e32 v224, v59, v224
	v_cvt_pk_bf16_f32 v193, v58, v59
	s_waitcnt lgkmcnt(6)
	v_mfma_f32_32x32x16_bf16 v[156:171], v[228:231], v[88:91], v[156:171]
	ds_read_b128 v[228:231], v153 offset:13440
	v_exp_f32_e32 v63, v63
	v_add_f32_e32 v224, v60, v224
	v_add_f32_e32 v224, v61, v224
	v_add_f32_e32 v224, v62, v224
	s_waitcnt lgkmcnt(6)
	v_mfma_f32_32x32x16_bf16 v[0:15], v[216:219], v[92:95], v[0:15]
	ds_read_b128 v[216:219], v153 offset:20096
	v_add_f32_e32 v224, v63, v224
	v_cvt_pk_bf16_f32 v194, v60, v61
	v_cvt_pk_bf16_f32 v195, v62, v63
	v_exp_f32_e32 v64, v64
	s_waitcnt lgkmcnt(6)
	v_mfma_f32_32x32x16_bf16 v[156:171], v[220:223], v[92:95], v[156:171]
	ds_read_b128 v[220:223], v153 offset:13472
	v_exp_f32_e32 v65, v65
	v_exp_f32_e32 v66, v66
	v_exp_f32_e32 v67, v67
	v_add_f32_e32 v224, v64, v224
	v_mfma_f32_32x32x16_bf16 v[32:47], v[248:251], v[192:195], v[32:47]
	ds_read_b64_tr_b16 v[248:249], v154 offset:31296
	ds_read_b64_tr_b16 v[250:251], v154 offset:32448
	v_exp_f32_e32 v68, v68
	v_add_f32_e32 v224, v65, v224
	v_cvt_pk_bf16_f32 v188, v64, v65
	v_exp_f32_e32 v69, v69
	s_waitcnt lgkmcnt(7)
	v_mfma_f32_32x32x16_bf16 v[16:31], v[236:239], v[192:195], v[16:31]
	ds_read_b64_tr_b16 v[236:237], v154 offset:33536
	ds_read_b64_tr_b16 v[238:239], v154 offset:34688
	v_add_f32_e32 v224, v66, v224
	v_exp_f32_e32 v70, v70
	v_add_f32_e32 v224, v67, v224
	v_cvt_pk_bf16_f32 v189, v66, v67
	s_waitcnt lgkmcnt(6)
	v_mfma_f32_32x32x16_bf16 v[0:15], v[228:231], v[104:107], v[0:15]
	ds_read_b128 v[228:231], v153 offset:20128
	v_exp_f32_e32 v71, v71
	v_add_f32_e32 v224, v68, v224
	v_exp_f32_e32 v72, v72
	v_add_f32_e32 v224, v69, v224
	s_waitcnt lgkmcnt(6)
	v_mfma_f32_32x32x16_bf16 v[156:171], v[216:219], v[104:107], v[156:171]
	v_cvt_pk_bf16_f32 v190, v68, v69
	v_exp_f32_e32 v73, v73
	v_add_f32_e32 v224, v70, v224
	v_exp_f32_e32 v74, v74
	s_waitcnt lgkmcnt(5)
	v_mfma_f32_32x32x16_bf16 v[0:15], v[220:223], v[108:111], v[0:15]
	v_add_f32_e32 v224, v71, v224
	v_cvt_pk_bf16_f32 v191, v70, v71
	v_exp_f32_e32 v75, v75
	v_add_f32_e32 v224, v72, v224
	s_nop 0
	v_mfma_f32_32x32x16_bf16 v[32:47], v[244:247], v[188:191], v[32:47]
	ds_read_b64_tr_b16 v[244:245], v154 offset:33600
	ds_read_b64_tr_b16 v[246:247], v154 offset:34752
	v_exp_f32_e32 v76, v76
	v_add_f32_e32 v224, v73, v224
	v_cvt_pk_bf16_f32 v192, v72, v73
	v_exp_f32_e32 v77, v77
	s_waitcnt lgkmcnt(5)
	v_mfma_f32_32x32x16_bf16 v[16:31], v[248:251], v[188:191], v[16:31]
	v_add_f32_e32 v224, v74, v224
	v_exp_f32_e32 v78, v78
	v_add_f32_e32 v224, v75, v224
	v_cvt_pk_bf16_f32 v193, v74, v75
	s_waitcnt lgkmcnt(2)
	v_mfma_f32_32x32x16_bf16 v[156:171], v[228:231], v[108:111], v[156:171]
	v_exp_f32_e32 v79, v79
	v_add_f32_e32 v224, v76, v224
	v_add_f32_e32 v224, v77, v224
	v_add_f32_e32 v224, v78, v224
	v_add_f32_e32 v224, v79, v224
	v_cvt_pk_bf16_f32 v194, v76, v77
	v_cvt_pk_bf16_f32 v195, v78, v79
	s_nop 1
	v_mfma_f32_32x32x16_bf16 v[32:47], v[236:239], v[192:195], v[32:47]
	s_waitcnt lgkmcnt(0)
	v_mfma_f32_32x32x16_bf16 v[16:31], v[244:247], v[192:195], v[16:31]
	v_add_f32_e32 v152, v152, v224
	s_waitcnt lgkmcnt(0)
	s_barrier
; #define MFMA32(a, b, c) __builtin_amdgcn_mfma_f32_32x32x16_bf16((a), (b), (c), 0, 0, 0)
; DI unsigned pk_bf16(float lo, float hi) { f32x2 v = {lo, hi}; bf2_t b = __builtin_convertvector(v, bf2_t); return __builtin_bit_cast(unsigned, b); }
; DI int crow(int i, int h) { return (i & 3) + 8 * (i >> 2) + 4 * h; }
; DI float fast_exp2(float x) { return __builtin_amdgcn_exp2f(x); }
; template <int DQK, bool SB, bool SMAX>
; DI void attn_item(const Params& p, char* smem, int bh, int qb, float Mb) {
;     ...
; #pragma unroll
;       for (int ks = 0; ks < NKS; ++ks)
; #pragma unroll
;         for (int kb = 0; kb < 2; ++kb) {
;           const bf16x8 a = *(const bf16x8*)(kc + (kb * 32 + r) * KSTR + ks * 16 + h * 8);
;           st[kb] = MFMA32(a, qf[ks], st[kb]);
;         }
;     }
;     __builtin_amdgcn_sched_barrier(0);
;     AT_WRITE(0, st2 ^ 1)
;     AT_LOAD(0, (it + 2 < nt) ? it + 2 : nt - 1)
;     if (active) {
;       const bool diag = (kb0 + 64 > qw0);
;       bf16x8 pk[4];
;       if (!SB) {
;         if (diag) {
; #pragma unroll
;           for (int kb = 0; kb < 2; ++kb)
; #pragma unroll
;             for (int i = 0; i < 16; ++i) { const int key = kb0 + kb * 32 + crow(i, h); if (key > query) st[kb][i] = -__builtin_huge_valf(); }
;         }
;         if (SMAX) {
;           float ps = 0.f;
; #pragma unroll
;           for (int kb = 0; kb < 2; ++kb)
; #pragma unroll
;             for (int i = 0; i < 16; ++i) { const float pv = fast_exp2(st[kb][i]); st[kb][i] = pv; ps += pv; }
;           lsum += ps;
;     ...
; #pragma unroll
;       for (int kb = 0; kb < 2; ++kb)
; #pragma unroll
;         for (int s = 0; s < 2; ++s) {
;           u32x4 w;
; #pragma unroll
;           for (int e = 0; e < 4; ++e) w[e] = pk_bf16(st[kb][8 * s + 2 * e], st[kb][8 * s + 2 * e + 1]);
;           pk[kb * 2 + s] = __builtin_bit_cast(bf16x8, w);
;         }
; #pragma unroll
;       for (int kk = 0; kk < 4; ++kk)
; #pragma unroll
;         for (int db = 0; db < 2; ++db) {
;           const s16x4 v0 = __builtin_amdgcn_ds_read_tr16_b64_v4i16((lds_s16x4*)(vc + voff + (16 * kk) * VSTR + 32 * db));
;           const s16x4 v1 = __builtin_amdgcn_ds_read_tr16_b64_v4i16((lds_s16x4*)(vc + voff + (16 * kk + 8) * VSTR + 32 * db));
;           const bf16x8 vf = __builtin_shufflevector(v0, v1, 0, 1, 2, 3, 4, 5, 6, 7);
;           O[db] = MFMA32(vf, pk[kk], O[db]);
;         }
	s_add_i32 s14, s14, 1
	s_setprio 0
	ds_read_b128 v[216:219], v153
	ds_read_b128 v[220:223], v153 offset:6656
	ds_read_b128 v[228:231], v153 offset:32
	ds_read_b64_tr_b16 v[236:237], v154 offset:35840
	ds_read_b64_tr_b16 v[238:239], v154 offset:36992
	ds_read_b64_tr_b16 v[244:245], v154 offset:35904
	ds_read_b64_tr_b16 v[246:247], v154 offset:37056
	ds_read_b64_tr_b16 v[248:249], v154 offset:38144
	ds_read_b64_tr_b16 v[250:251], v154 offset:39296
	s_min_i32 s2, s14, s4
	s_mul_i32 s3, s2, 0x3000
	s_add_u32 s30, s22, s3
	s_addc_u32 s31, s23, 0
	s_add_u32 s34, s30, 0x1000
	s_addc_u32 s35, s31, 0
	s_add_i32 s3, s14, -1
	s_min_i32 s3, s3, s4
	s_lshl_b32 s3, s3, 13
	s_add_u32 s36, s38, s3
	s_addc_u32 s37, s39, 0
	global_load_dwordx4 v[112:115], v174, s[30:31] offset:-4096
	global_load_dwordx4 v[116:119], v174, s[30:31]
	global_load_dwordx4 v[120:123], v174, s[34:35]
	global_load_dwordx4 v[124:127], v174, s[36:37] offset:-4096
	global_load_dwordx4 v[128:131], v174, s[36:37]
	s_setprio 2
	s_waitcnt vmcnt(9)
	ds_write_b128 v206, v[132:135] offset:13312
	s_waitcnt vmcnt(8)
	ds_write_b128 v207, v[136:139] offset:13312
	s_waitcnt vmcnt(7)
	ds_write_b128 v208, v[140:143] offset:13312
	s_waitcnt vmcnt(6)
	ds_write_b128 v203, v[144:147] offset:26624
	s_waitcnt vmcnt(5)
	ds_write_b128 v203, v[148:151] offset:31232
	v_exp_f32_e32 v0, v0
	v_exp_f32_e32 v1, v1
	v_exp_f32_e32 v2, v2
	v_exp_f32_e32 v3, v3
	s_waitcnt lgkmcnt(13)
	v_mfma_f32_32x32x16_bf16 v[48:63], v[216:219], v[80:83], 0
	ds_read_b128 v[216:219], v153 offset:6688
	v_exp_f32_e32 v4, v4
	v_add_f32_e32 v224, v1, v0
	v_cvt_pk_bf16_f32 v188, v0, v1
	v_exp_f32_e32 v5, v5
	s_waitcnt lgkmcnt(13)
	v_mfma_f32_32x32x16_bf16 v[64:79], v[220:223], v[80:83], 0
	ds_read_b128 v[220:223], v153 offset:64
	v_add_f32_e32 v224, v2, v224
	v_exp_f32_e32 v6, v6
	v_add_f32_e32 v224, v3, v224
	v_cvt_pk_bf16_f32 v189, v2, v3
	s_waitcnt lgkmcnt(13)
	v_mfma_f32_32x32x16_bf16 v[48:63], v[228:231], v[84:87], v[48:63]
	ds_read_b128 v[228:231], v153 offset:6720
	v_exp_f32_e32 v7, v7
	v_add_f32_e32 v224, v4, v224
	v_exp_f32_e32 v8, v8
	v_add_f32_e32 v224, v5, v224
	s_waitcnt lgkmcnt(2)
	v_mfma_f32_32x32x16_bf16 v[64:79], v[216:219], v[84:87], v[64:79]
	ds_read_b128 v[216:219], v153 offset:96
	v_cvt_pk_bf16_f32 v190, v4, v5
	v_exp_f32_e32 v9, v9
	v_add_f32_e32 v224, v6, v224
	v_exp_f32_e32 v10, v10
	s_waitcnt lgkmcnt(2)
	v_mfma_f32_32x32x16_bf16 v[48:63], v[220:223], v[88:91], v[48:63]
	ds_read_b128 v[220:223], v153 offset:6752
	v_add_f32_e32 v224, v7, v224
	v_cvt_pk_bf16_f32 v191, v6, v7
	v_exp_f32_e32 v11, v11
	v_add_f32_e32 v224, v8, v224
	s_nop 0
	v_mfma_f32_32x32x16_bf16 v[32:47], v[236:239], v[188:191], v[32:47]
	ds_read_b64_tr_b16 v[236:237], v154 offset:38208
	ds_read_b64_tr_b16 v[238:239], v154 offset:39360
	v_exp_f32_e32 v12, v12
	v_add_f32_e32 v224, v9, v224
	v_cvt_pk_bf16_f32 v192, v8, v9
	v_exp_f32_e32 v13, v13
	v_mfma_f32_32x32x16_bf16 v[16:31], v[244:247], v[188:191], v[16:31]
	ds_read_b64_tr_b16 v[244:245], v154 offset:40448
	ds_read_b64_tr_b16 v[246:247], v154 offset:41600
	v_add_f32_e32 v224, v10, v224
	v_exp_f32_e32 v14, v14
	v_add_f32_e32 v224, v11, v224
	v_cvt_pk_bf16_f32 v193, v10, v11
	s_waitcnt lgkmcnt(6)
	v_mfma_f32_32x32x16_bf16 v[64:79], v[228:231], v[88:91], v[64:79]
	ds_read_b128 v[228:231], v153 offset:128
	v_exp_f32_e32 v15, v15
	v_add_f32_e32 v224, v12, v224
	v_add_f32_e32 v224, v13, v224
	v_add_f32_e32 v224, v14, v224
	s_waitcnt lgkmcnt(6)
	v_mfma_f32_32x32x16_bf16 v[48:63], v[216:219], v[92:95], v[48:63]
	ds_read_b128 v[216:219], v153 offset:6784
	v_add_f32_e32 v224, v15, v224
	v_cvt_pk_bf16_f32 v194, v12, v13
	v_cvt_pk_bf16_f32 v195, v14, v15
	v_exp_f32_e32 v156, v156
	s_waitcnt lgkmcnt(6)
	v_mfma_f32_32x32x16_bf16 v[64:79], v[220:223], v[92:95], v[64:79]
	ds_read_b128 v[220:223], v153 offset:160
	v_exp_f32_e32 v157, v157
	v_exp_f32_e32 v158, v158
	v_exp_f32_e32 v159, v159
	v_add_f32_e32 v224, v156, v224
	v_mfma_f32_32x32x16_bf16 v[32:47], v[248:251], v[192:195], v[32:47]
	ds_read_b64_tr_b16 v[248:249], v154 offset:40512
	ds_read_b64_tr_b16 v[250:251], v154 offset:41664
	v_exp_f32_e32 v160, v160
	v_add_f32_e32 v224, v157, v224
	v_cvt_pk_bf16_f32 v188, v156, v157
	v_exp_f32_e32 v161, v161
	s_waitcnt lgkmcnt(7)
	v_mfma_f32_32x32x16_bf16 v[16:31], v[236:239], v[192:195], v[16:31]
	ds_read_b64_tr_b16 v[236:237], v154 offset:42752
	ds_read_b64_tr_b16 v[238:239], v154 offset:43904
	v_add_f32_e32 v224, v158, v224
	v_exp_f32_e32 v162, v162
	v_add_f32_e32 v224, v159, v224
	v_cvt_pk_bf16_f32 v189, v158, v159
	s_waitcnt lgkmcnt(6)
	v_mfma_f32_32x32x16_bf16 v[48:63], v[228:231], v[104:107], v[48:63]
	ds_read_b128 v[228:231], v153 offset:6816
	v_exp_f32_e32 v163, v163
	v_add_f32_e32 v224, v160, v224
	v_exp_f32_e32 v164, v164
	v_add_f32_e32 v224, v161, v224
	s_waitcnt lgkmcnt(6)
	v_mfma_f32_32x32x16_bf16 v[64:79], v[216:219], v[104:107], v[64:79]
	v_cvt_pk_bf16_f32 v190, v160, v161
	v_exp_f32_e32 v165, v165
	v_add_f32_e32 v224, v162, v224
	v_exp_f32_e32 v166, v166
	s_waitcnt lgkmcnt(5)
	v_mfma_f32_32x32x16_bf16 v[48:63], v[220:223], v[108:111], v[48:63]
	v_add_f32_e32 v224, v163, v224
	v_cvt_pk_bf16_f32 v191, v162, v163
	v_exp_f32_e32 v167, v167
	v_add_f32_e32 v224, v164, v224
	s_nop 0
	v_mfma_f32_32x32x16_bf16 v[32:47], v[244:247], v[188:191], v[32:47]
	ds_read_b64_tr_b16 v[244:245], v154 offset:42816
	ds_read_b64_tr_b16 v[246:247], v154 offset:43968
	v_exp_f32_e32 v168, v168
	v_add_f32_e32 v224, v165, v224
	v_cvt_pk_bf16_f32 v192, v164, v165
	v_exp_f32_e32 v169, v169
	s_waitcnt lgkmcnt(5)
	v_mfma_f32_32x32x16_bf16 v[16:31], v[248:251], v[188:191], v[16:31]
	v_add_f32_e32 v224, v166, v224
	v_exp_f32_e32 v170, v170
	v_add_f32_e32 v224, v167, v224
	v_cvt_pk_bf16_f32 v193, v166, v167
	s_waitcnt lgkmcnt(2)
	v_mfma_f32_32x32x16_bf16 v[64:79], v[228:231], v[108:111], v[64:79]
	v_exp_f32_e32 v171, v171
	v_add_f32_e32 v224, v168, v224
	v_add_f32_e32 v224, v169, v224
	v_add_f32_e32 v224, v170, v224
	v_add_f32_e32 v224, v171, v224
	v_cvt_pk_bf16_f32 v194, v168, v169
	v_cvt_pk_bf16_f32 v195, v170, v171
	s_nop 1
	v_mfma_f32_32x32x16_bf16 v[32:47], v[236:239], v[192:195], v[32:47]
	s_waitcnt lgkmcnt(0)
	v_mfma_f32_32x32x16_bf16 v[16:31], v[244:247], v[192:195], v[16:31]
	v_add_f32_e32 v152, v152, v224
	s_waitcnt lgkmcnt(0)
	s_barrier
	s_add_i32 s14, s14, 1
	s_add_i32 s21, s21, -1
	s_cmp_lg_u32 s21, 0
	s_cbranch_scc1 .Lt15_loop
